# v71 + G4 gate GEMM k-loops rewritten with the v3 schedule (pipelined LDS reads, SGPR-base DMA, DMA 1.5 iterations ahead) using registers dead during the gate loop
# speedup vs baseline: 1.0243x; 1.0224x over previous
.LBB0_161:
	v_mov_b32_e32 v4, v168
	s_waitcnt vmcnt(0)
	s_waitcnt lgkmcnt(0)
	v_mov_b32_e32 v40, 0
	v_readfirstlane_b32 s2, v4
	v_lshrrev_b32_e32 v5, 4, v4
	v_and_b32_e32 v6, 7, v4
	s_lshl_b32 s3, s2, 5
	v_lshlrev_b32_e32 v4, 6, v4
	s_lshl_b32 s2, s2, 6
	v_bitop3_b32 v5, v5, v6, 3 bitop3:0x6c
	s_and_b32 s3, s3, 0xfffff000
	v_and_b32_e32 v4, 0x3c0, v4
	s_and_b32 s2, s2, 0x1000
	v_lshlrev_b32_e32 v71, 3, v5
	v_or_b32_e32 v5, s3, v4
	v_or_b32_e32 v4, s2, v4
	v_xor_b32_e32 v69, 32, v71
	s_mov_b64 s[58:59], 0
	s_mov_b32 s67, 0
	v_lshlrev_b32_e32 v70, 1, v5
	v_lshlrev_b32_e32 v68, 1, v4
	v_mov_b32_e32 v41, v40
	v_mov_b32_e32 v42, v40
	v_mov_b32_e32 v43, v40
	v_mov_b32_e32 v52, v40
	v_mov_b32_e32 v53, v40
	v_mov_b32_e32 v54, v40
	v_mov_b32_e32 v55, v40
	v_mov_b32_e32 v4, v40
	v_mov_b32_e32 v5, v40
	v_mov_b32_e32 v6, v40
	v_mov_b32_e32 v7, v40
	v_mov_b32_e32 v8, v40
	v_mov_b32_e32 v9, v40
	v_mov_b32_e32 v10, v40
	v_mov_b32_e32 v11, v40
	v_mov_b32_e32 v12, v40
	v_mov_b32_e32 v13, v40
	v_mov_b32_e32 v14, v40
	v_mov_b32_e32 v15, v40
	v_mov_b32_e32 v16, v40
	v_mov_b32_e32 v17, v40
	v_mov_b32_e32 v18, v40
	v_mov_b32_e32 v19, v40
	v_mov_b32_e32 v20, v40
	v_mov_b32_e32 v21, v40
	v_mov_b32_e32 v22, v40
	v_mov_b32_e32 v23, v40
	v_mov_b32_e32 v24, v40
	v_mov_b32_e32 v25, v40
	v_mov_b32_e32 v26, v40
	v_mov_b32_e32 v27, v40
	v_mov_b32_e32 v28, v40
	v_mov_b32_e32 v29, v40
	v_mov_b32_e32 v30, v40
	v_mov_b32_e32 v31, v40
	v_mov_b32_e32 v32, v40
	v_mov_b32_e32 v33, v40
	v_mov_b32_e32 v34, v40
	v_mov_b32_e32 v35, v40
	v_mov_b32_e32 v36, v40
	v_mov_b32_e32 v37, v40
	v_mov_b32_e32 v38, v40
	v_mov_b32_e32 v39, v40
	v_mov_b32_e32 v44, v40
	v_mov_b32_e32 v45, v40
	v_mov_b32_e32 v46, v40
	v_mov_b32_e32 v47, v40
	v_mov_b32_e32 v48, v40
	v_mov_b32_e32 v49, v40
	v_mov_b32_e32 v50, v40
	v_mov_b32_e32 v51, v40
	v_mov_b32_e32 v56, v40
	v_mov_b32_e32 v57, v40
	v_mov_b32_e32 v58, v40
	v_mov_b32_e32 v59, v40
	v_mov_b32_e32 v60, v40
	v_mov_b32_e32 v61, v40
	v_mov_b32_e32 v62, v40
	v_mov_b32_e32 v63, v40
	v_mov_b32_e32 v64, v40
	v_mov_b32_e32 v65, v40
	v_mov_b32_e32 v66, v40
	v_mov_b32_e32 v67, v40
	s_waitcnt vmcnt(0) lgkmcnt(0)
	s_barrier
	v_lshlrev_b32_e32 v126, 1, v71
	v_add_u32_e32 v234, v70, v126
	v_add_u32_e32 v236, v68, v126
	v_lshlrev_b32_e32 v126, 1, v69
	v_add_u32_e32 v235, v70, v126
	v_add_u32_e32 v237, v68, v126
	v_lshrrev_b32_e32 v127, 3, v168
	v_xor_b32_e32 v126, v127, v168
	v_and_b32_e32 v126, 7, v126
	v_lshlrev_b32_e32 v126, 4, v126
	s_movk_i32 s77, 0x800
	v_mad_u32_u24 v238, v127, s77, v126
	v_add_u32_e32 v239, 0x10000, v238
	v_add_u32_e32 v240, 0x20000, v238
	v_add_u32_e32 v241, 0x30000, v238
	s_add_u32 s34, s52, s68
	s_addc_u32 s35, s53, s69
	s_add_u32 s94, s54, 0x780080
	s_addc_u32 s95, s55, 0
	v_readfirstlane_b32 s77, v168
	s_lshl_b32 s77, s77, 4
	s_or_b32 s77, s77, 0x8000
	s_mov_b32 m0, s77
	s_nop 0
	global_load_lds_dwordx4 v238, s[34:35]
	s_add_u32 m0, s77, 0x1000
	s_nop 0
	global_load_lds_dwordx4 v239, s[34:35]
	s_add_u32 m0, s77, 0x2000
	s_nop 0
	global_load_lds_dwordx4 v240, s[34:35]
	s_add_u32 m0, s77, 0x3000
	s_nop 0
	global_load_lds_dwordx4 v241, s[34:35]
	s_add_u32 m0, s77, 0x4000
	s_nop 0
	global_load_lds_dwordx4 v238, s[94:95]
	s_add_u32 m0, s77, 0x5000
	s_nop 0
	global_load_lds_dwordx4 v239, s[94:95]
	s_add_u32 m0, s77, 0x6000
	s_nop 0
	global_load_lds_dwordx4 v240, s[94:95]
	s_add_u32 m0, s77, 0x7000
	s_nop 0
	global_load_lds_dwordx4 v241, s[94:95]
	s_add_u32 s34, s34, 0x80
	s_addc_u32 s35, s35, 0
	s_add_u32 s94, s94, 0x80
	s_addc_u32 s95, s95, 0
	s_xor_b32 s77, s77, 0x8000
.LBB0_162:
	s_waitcnt vmcnt(8)
	s_barrier
	ds_read_b128 v[94:97], v234
	ds_read_b128 v[98:101], v234 offset:2048
	ds_read_b128 v[102:105], v234 offset:4096
	ds_read_b128 v[106:109], v234 offset:6144
	ds_read_b128 v[110:113], v236 offset:16384
	ds_read_b128 v[114:117], v236 offset:18432
	ds_read_b128 v[118:121], v236 offset:20480
	ds_read_b128 v[122:125], v236 offset:22528
	ds_read_b128 v[202:205], v235
	ds_read_b128 v[206:209], v235 offset:2048
	ds_read_b128 v[210:213], v235 offset:4096
	ds_read_b128 v[214:217], v235 offset:6144
	ds_read_b128 v[218:221], v237 offset:16384
	ds_read_b128 v[222:225], v237 offset:18432
	ds_read_b128 v[226:229], v237 offset:20480
	s_waitcnt lgkmcnt(10)
	v_mfma_f32_16x16x32_bf16 v[64:67], v[110:113], v[94:97], v[64:67]
	v_mfma_f32_16x16x32_bf16 v[60:63], v[110:113], v[98:101], v[60:63]
	v_mfma_f32_16x16x32_bf16 v[56:59], v[110:113], v[102:105], v[56:59]
	v_mfma_f32_16x16x32_bf16 v[48:51], v[110:113], v[106:109], v[48:51]
	ds_read_b128 v[230:233], v237 offset:22528
	s_waitcnt lgkmcnt(10)
	v_mfma_f32_16x16x32_bf16 v[44:47], v[114:117], v[94:97], v[44:47]
	v_mfma_f32_16x16x32_bf16 v[36:39], v[114:117], v[98:101], v[36:39]
	v_mfma_f32_16x16x32_bf16 v[32:35], v[114:117], v[102:105], v[32:35]
	v_mfma_f32_16x16x32_bf16 v[28:31], v[114:117], v[106:109], v[28:31]
	v_xor_b32_e32 v234, 0x8000, v234
	v_xor_b32_e32 v236, 0x8000, v236
	s_waitcnt lgkmcnt(9)
	v_mfma_f32_16x16x32_bf16 v[24:27], v[118:121], v[94:97], v[24:27]
	v_mfma_f32_16x16x32_bf16 v[20:23], v[118:121], v[98:101], v[20:23]
	v_mfma_f32_16x16x32_bf16 v[16:19], v[118:121], v[102:105], v[16:19]
	v_mfma_f32_16x16x32_bf16 v[12:15], v[118:121], v[106:109], v[12:15]
	v_xor_b32_e32 v235, 0x8000, v235
	v_xor_b32_e32 v237, 0x8000, v237
	s_waitcnt lgkmcnt(8)
	v_mfma_f32_16x16x32_bf16 v[8:11], v[122:125], v[94:97], v[8:11]
	v_mfma_f32_16x16x32_bf16 v[4:7], v[122:125], v[98:101], v[4:7]
	v_mfma_f32_16x16x32_bf16 v[52:55], v[122:125], v[102:105], v[52:55]
	v_mfma_f32_16x16x32_bf16 v[40:43], v[122:125], v[106:109], v[40:43]
	s_waitcnt lgkmcnt(0)
	s_barrier
	s_cmp_eq_u32 s58, 0x700
	s_cbranch_scc1 .Lv3_nodma_G4
	s_mov_b32 m0, s77
	v_mfma_f32_16x16x32_bf16 v[64:67], v[218:221], v[202:205], v[64:67]
	global_load_lds_dwordx4 v238, s[34:35]
	s_add_u32 m0, s77, 0x1000
	v_mfma_f32_16x16x32_bf16 v[60:63], v[218:221], v[206:209], v[60:63]
	global_load_lds_dwordx4 v239, s[34:35]
	s_add_u32 m0, s77, 0x2000
	v_mfma_f32_16x16x32_bf16 v[56:59], v[218:221], v[210:213], v[56:59]
	global_load_lds_dwordx4 v240, s[34:35]
	s_add_u32 m0, s77, 0x3000
	v_mfma_f32_16x16x32_bf16 v[48:51], v[218:221], v[214:217], v[48:51]
	global_load_lds_dwordx4 v241, s[34:35]
	s_add_u32 m0, s77, 0x4000
	v_mfma_f32_16x16x32_bf16 v[44:47], v[222:225], v[202:205], v[44:47]
	global_load_lds_dwordx4 v238, s[94:95]
	s_add_u32 m0, s77, 0x5000
	v_mfma_f32_16x16x32_bf16 v[36:39], v[222:225], v[206:209], v[36:39]
	global_load_lds_dwordx4 v239, s[94:95]
	s_add_u32 m0, s77, 0x6000
	v_mfma_f32_16x16x32_bf16 v[32:35], v[222:225], v[210:213], v[32:35]
	global_load_lds_dwordx4 v240, s[94:95]
	s_add_u32 m0, s77, 0x7000
	v_mfma_f32_16x16x32_bf16 v[28:31], v[222:225], v[214:217], v[28:31]
	global_load_lds_dwordx4 v241, s[94:95]
	s_add_u32 s34, s34, 0x80
	s_addc_u32 s35, s35, 0
	s_add_u32 s94, s94, 0x80
	s_addc_u32 s95, s95, 0
	s_xor_b32 s77, s77, 0x8000
	s_branch .Lv3_join_G4
.Lv3_nodma_G4:
	v_mfma_f32_16x16x32_bf16 v[64:67], v[218:221], v[202:205], v[64:67]
	v_mfma_f32_16x16x32_bf16 v[60:63], v[218:221], v[206:209], v[60:63]
	v_mfma_f32_16x16x32_bf16 v[56:59], v[218:221], v[210:213], v[56:59]
	v_mfma_f32_16x16x32_bf16 v[48:51], v[218:221], v[214:217], v[48:51]
	v_mfma_f32_16x16x32_bf16 v[44:47], v[222:225], v[202:205], v[44:47]
	v_mfma_f32_16x16x32_bf16 v[36:39], v[222:225], v[206:209], v[36:39]
	v_mfma_f32_16x16x32_bf16 v[32:35], v[222:225], v[210:213], v[32:35]
	v_mfma_f32_16x16x32_bf16 v[28:31], v[222:225], v[214:217], v[28:31]
.Lv3_join_G4:
	s_add_u32 s58, s58, 0x80
	s_cmpk_eq_i32 s58, 0x780
	v_mfma_f32_16x16x32_bf16 v[24:27], v[226:229], v[202:205], v[24:27]
	v_mfma_f32_16x16x32_bf16 v[20:23], v[226:229], v[206:209], v[20:23]
	v_mfma_f32_16x16x32_bf16 v[16:19], v[226:229], v[210:213], v[16:19]
	v_mfma_f32_16x16x32_bf16 v[12:15], v[226:229], v[214:217], v[12:15]
	v_mfma_f32_16x16x32_bf16 v[8:11], v[230:233], v[202:205], v[8:11]
	v_mfma_f32_16x16x32_bf16 v[4:7], v[230:233], v[206:209], v[4:7]
	v_mfma_f32_16x16x32_bf16 v[52:55], v[230:233], v[210:213], v[52:55]
	v_mfma_f32_16x16x32_bf16 v[40:43], v[230:233], v[214:217], v[40:43]
	s_cbranch_scc0 .LBB0_162
	s_waitcnt vmcnt(0)
	s_barrier
	s_mov_b32 s60, 0x8000
	v_lshl_add_u32 v71, v71, 1, s60
	v_add_u32_e32 v84, v71, v70
	v_add_u32_e32 v71, v71, v68
	ds_read_b128 v[72:75], v84
	ds_read_b128 v[76:79], v84 offset:2048
	ds_read_b128 v[80:83], v84 offset:4096
	ds_read_b128 v[84:87], v84 offset:6144
	ds_read_b128 v[88:91], v71 offset:16384
	ds_read_b128 v[92:95], v71 offset:18432
	ds_read_b128 v[96:99], v71 offset:20480
	ds_read_b128 v[100:103], v71 offset:22528
	s_waitcnt lgkmcnt(3)
	v_mfma_f32_16x16x32_bf16 v[60:63], v[88:91], v[76:79], v[60:63]
	s_cmp_eq_u32 s66, 1
	s_mov_b32 s2, 0x6c50000
	s_cselect_b32 s20, s2, 0x4450000
	s_waitcnt lgkmcnt(2)
	v_mfma_f32_16x16x32_bf16 v[36:39], v[92:95], v[76:79], v[36:39]
	s_and_b64 s[2:3], s[56:57], exec
	s_cselect_b32 s20, 0x9530000, s20
	s_add_u32 s56, s80, s20
	s_waitcnt lgkmcnt(1)
	v_mfma_f32_16x16x32_bf16 v[20:23], v[96:99], v[76:79], v[20:23]
	s_addc_u32 s57, s81, 0
	s_lshl_b32 s2, s66, 20
	s_add_u32 s58, s82, s2
	s_waitcnt lgkmcnt(0)
	v_mfma_f32_16x16x32_bf16 v[4:7], v[100:103], v[76:79], v[4:7]
	s_mov_b64 s[20:21], 0x8000
	s_mov_b64 s[34:35], 0x18000
	s_addc_u32 s59, s83, 0
	v_mfma_f32_16x16x32_bf16 v[76:79], v[100:103], v[84:87], v[40:43]
	s_nop 2
	v_lshl_add_u32 v40, v69, 1, s60
	v_mfma_f32_16x16x32_bf16 v[64:67], v[88:91], v[72:75], v[64:67]
	v_add_u32_e32 v41, v40, v70
	v_mfma_f32_16x16x32_bf16 v[44:47], v[92:95], v[72:75], v[44:47]
	v_mfma_f32_16x16x32_bf16 v[24:27], v[96:99], v[72:75], v[24:27]
	v_mfma_f32_16x16x32_bf16 v[8:11], v[100:103], v[72:75], v[8:11]
	v_mfma_f32_16x16x32_bf16 v[72:75], v[100:103], v[80:83], v[52:55]
	s_nop 2
	v_add_u32_e32 v52, v40, v68
	v_mfma_f32_16x16x32_bf16 v[56:59], v[88:91], v[80:83], v[56:59]
	v_mfma_f32_16x16x32_bf16 v[48:51], v[88:91], v[84:87], v[48:51]
	v_mfma_f32_16x16x32_bf16 v[32:35], v[92:95], v[80:83], v[32:35]
	v_mfma_f32_16x16x32_bf16 v[28:31], v[92:95], v[84:87], v[28:31]
	v_mfma_f32_16x16x32_bf16 v[16:19], v[96:99], v[80:83], v[16:19]
	v_mfma_f32_16x16x32_bf16 v[12:15], v[96:99], v[84:87], v[12:15]
	ds_read_b128 v[80:83], v41
	ds_read_b128 v[84:87], v41 offset:2048
	ds_read_b128 v[88:91], v41 offset:4096
	ds_read_b128 v[92:95], v41 offset:6144
	ds_read_b128 v[40:43], v52 offset:16384
	ds_read_b128 v[68:71], v52 offset:18432
	ds_read_b128 v[96:99], v52 offset:20480
	ds_read_b128 v[100:103], v52 offset:22528
	s_waitcnt vmcnt(0)
	s_waitcnt lgkmcnt(3)
	v_mfma_f32_16x16x32_bf16 v[64:67], v[40:43], v[80:83], v[64:67]
	s_waitcnt lgkmcnt(0)
	s_barrier
	v_mfma_f32_16x16x32_bf16 v[60:63], v[40:43], v[84:87], v[60:63]
	v_mfma_f32_16x16x32_bf16 v[56:59], v[40:43], v[88:91], v[56:59]
	v_mfma_f32_16x16x32_bf16 v[52:55], v[40:43], v[92:95], v[48:51]
	v_mfma_f32_16x16x32_bf16 v[40:43], v[68:71], v[88:91], v[32:35]
	v_mfma_f32_16x16x32_bf16 v[32:35], v[96:99], v[80:83], v[24:27]
	v_mfma_f32_16x16x32_bf16 v[24:27], v[96:99], v[88:91], v[16:19]
	v_mfma_f32_16x16x32_bf16 v[16:19], v[100:103], v[80:83], v[8:11]
	v_mfma_f32_16x16x32_bf16 v[8:11], v[100:103], v[88:91], v[72:75]
	s_nop 2
	v_mov_b32_e32 v74, v168
	v_mfma_f32_16x16x32_bf16 v[48:51], v[68:71], v[80:83], v[44:47]
	v_mov_b32_e32 v73, v2
	v_mfma_f32_16x16x32_bf16 v[44:47], v[68:71], v[84:87], v[36:39]
	v_mfma_f32_16x16x32_bf16 v[36:39], v[68:71], v[92:95], v[28:31]
	v_ashrrev_i32_e32 v68, 3, v74
	v_xor_b32_e32 v72, v68, v74
	v_ashrrev_i32_e32 v69, 31, v68
	v_mfma_f32_16x16x32_bf16 v[28:31], v[96:99], v[84:87], v[20:23]
	v_lshlrev_b64 v[68:69], 10, v[68:69]
	v_lshlrev_b32_e32 v72, 4, v72
	v_lshl_add_u64 v[70:71], s[56:57], 0, v[68:69]
	v_mfma_f32_16x16x32_bf16 v[20:23], v[96:99], v[92:95], v[12:15]
	v_and_b32_e32 v72, 0x70, v72
	v_lshl_add_u64 v[70:71], v[70:71], 0, v[72:73]
	v_lshl_add_u64 v[68:69], s[58:59], 0, v[68:69]
	v_mfma_f32_16x16x32_bf16 v[12:15], v[100:103], v[84:87], v[4:7]
	v_lshl_add_u64 v[68:69], v[68:69], 0, v[72:73]
	v_mfma_f32_16x16x32_bf16 v[4:7], v[100:103], v[92:95], v[76:79]
	s_nop 2
	v_lshlrev_b32_e32 v76, 4, v74
	v_add_u32_e32 v77, 0x1000, v76
	v_readfirstlane_b32 s2, v76
	s_mov_b32 m0, s2
	v_readfirstlane_b32 s2, v77
	v_add_u32_e32 v77, 0x2000, v76
	global_load_lds_dwordx4 v[70:71], off
	v_lshl_add_u64 v[74:75], v[70:71], 0, s[20:21]
	s_mov_b32 m0, s2
	v_readfirstlane_b32 s2, v77
	global_load_lds_dwordx4 v[74:75], off
	v_lshl_add_u64 v[74:75], v[70:71], 0, s[24:25]
	s_mov_b32 m0, s2
	v_lshl_add_u64 v[70:71], v[70:71], 0, s[34:35]
	global_load_lds_dwordx4 v[74:75], off
	v_add_u32_e32 v74, 0x3000, v76
	v_add_u32_e32 v72, 0x5000, v76
	v_readfirstlane_b32 s2, v74
	s_mov_b32 m0, s2
	s_nop 0
	global_load_lds_dwordx4 v[70:71], off
	v_add_u32_e32 v70, 0x4000, v76
	s_nop 0
	v_readfirstlane_b32 s2, v70
	s_mov_b32 m0, s2
	v_readfirstlane_b32 s2, v72
	v_add_u32_e32 v72, 0x6000, v76
	global_load_lds_dwordx4 v[68:69], off
	v_lshl_add_u64 v[70:71], v[68:69], 0, s[20:21]
	s_mov_b32 m0, s2
	v_readfirstlane_b32 s2, v72
	global_load_lds_dwordx4 v[70:71], off
	v_lshl_add_u64 v[70:71], v[68:69], 0, s[24:25]
	s_mov_b32 m0, s2
	v_lshl_add_u64 v[68:69], v[68:69], 0, s[34:35]
	global_load_lds_dwordx4 v[70:71], off
	v_add_u32_e32 v70, 0x7000, v76
	s_nop 0
	v_readfirstlane_b32 s2, v70
	s_mov_b32 m0, s2
	s_nop 0
	global_load_lds_dwordx4 v[68:69], off
	v_mov_b32_e32 v68, v168
	v_mov_b32_e32 v79, v168
	v_readfirstlane_b32 s2, v68
	v_lshrrev_b32_e32 v69, 4, v68
	v_and_b32_e32 v70, 7, v68
	v_lshlrev_b32_e32 v68, 6, v68
	s_waitcnt vmcnt(0)
	s_waitcnt vmcnt(0) lgkmcnt(0)
	s_barrier
	v_and_b32_e32 v77, 0x3c0, v68
	v_bitop3_b32 v76, v69, v70, 3 bitop3:0x6c
	v_ashrrev_i32_e32 v68, 3, v79
	v_xor_b32_e32 v72, v68, v79
	v_ashrrev_i32_e32 v69, 31, v68
	s_lshl_b32 s3, s2, 5
	s_lshl_b32 s2, s2, 6
	v_lshlrev_b64 v[68:69], 10, v[68:69]
	v_lshlrev_b32_e32 v72, 4, v72
	v_lshlrev_b32_e32 v79, 4, v79
	s_and_b32 s2, s2, 0x1000
	v_lshl_add_u64 v[70:71], s[56:57], 0, v[68:69]
	v_and_b32_e32 v72, 0x70, v72
	v_add_u32_e32 v80, 0x8000, v79
	v_or_b32_e32 v78, s2, v77
	v_lshl_add_u64 v[70:71], v[70:71], 0, v[72:73]
	v_readfirstlane_b32 s2, v80
	v_add_u32_e32 v80, 0x9000, v79
	v_lshl_add_u64 v[74:75], v[70:71], 0, s[22:23]
	s_mov_b32 m0, s2
	s_mov_b64 s[20:21], 0x8080
	v_readfirstlane_b32 s2, v80
	v_add_u32_e32 v80, 0xa000, v79
	global_load_lds_dwordx4 v[74:75], off
	v_lshl_add_u64 v[74:75], v[70:71], 0, s[20:21]
	s_mov_b32 m0, s2
	s_mov_b64 s[34:35], 0x10080
	v_readfirstlane_b32 s2, v80
	global_load_lds_dwordx4 v[74:75], off
	v_lshl_add_u64 v[74:75], v[70:71], 0, s[34:35]
	s_mov_b32 m0, s2
	v_lshl_add_u64 v[68:69], s[58:59], 0, v[68:69]
	global_load_lds_dwordx4 v[74:75], off
	v_add_u32_e32 v74, 0xb000, v79
	s_mov_b64 s[60:61], 0x18080
	v_readfirstlane_b32 s2, v74
	v_lshl_add_u64 v[68:69], v[68:69], 0, v[72:73]
	v_add_u32_e32 v72, 0xc000, v79
	v_lshl_add_u64 v[70:71], v[70:71], 0, s[60:61]
	s_mov_b32 m0, s2
	v_readfirstlane_b32 s2, v72
	v_add_u32_e32 v72, 0xd000, v79
	global_load_lds_dwordx4 v[70:71], off
	v_lshl_add_u64 v[70:71], v[68:69], 0, s[22:23]
	s_mov_b32 m0, s2
	v_readfirstlane_b32 s2, v72
	v_add_u32_e32 v72, 0xe000, v79
	global_load_lds_dwordx4 v[70:71], off
	v_lshl_add_u64 v[70:71], v[68:69], 0, s[20:21]
	s_mov_b32 m0, s2
	v_readfirstlane_b32 s2, v72
	global_load_lds_dwordx4 v[70:71], off
	v_lshl_add_u64 v[70:71], v[68:69], 0, s[34:35]
	s_mov_b32 m0, s2
	v_lshl_add_u64 v[68:69], v[68:69], 0, s[60:61]
	global_load_lds_dwordx4 v[70:71], off
	v_add_u32_e32 v70, 0xf000, v79
	v_lshlrev_b32_e32 v71, 4, v76
	v_readfirstlane_b32 s2, v70
	s_mov_b32 m0, s2
	s_and_b32 s3, s3, 0x7ffff000
	global_load_lds_dwordx4 v[68:69], off
	v_lshlrev_b32_e32 v69, 1, v78
	v_or_b32_e32 v68, v71, v69
	ds_read_b128 v[72:75], v68 offset:16384
	ds_read_b128 v[104:107], v68 offset:18432
	ds_read_b128 v[120:123], v68 offset:20480
	ds_read_b128 v[202:205], v68 offset:22528
	v_or_b32_e32 v70, s3, v77
	v_lshlrev_b32_e32 v163, 1, v70
	v_or_b32_e32 v70, v71, v163
	ds_read_b128 v[76:79], v70
	ds_read_b128 v[84:87], v70 offset:2048
	ds_read_b128 v[92:95], v70 offset:4096
	ds_read_b128 v[100:103], v70 offset:6144
	v_bitop3_b32 v69, v71, v69, 64 bitop3:0xde
	ds_read_b128 v[206:209], v69 offset:16384
	v_bitop3_b32 v71, v71, v163, 64 bitop3:0xde
	s_waitcnt lgkmcnt(0)
	v_mfma_f32_16x16x32_bf16 v[80:83], v[72:75], v[76:79], 0
	ds_read_b128 v[210:213], v71 offset:2048
	ds_read_b128 v[214:217], v71 offset:4096
	ds_read_b128 v[218:221], v71 offset:6144
	v_mfma_f32_16x16x32_bf16 v[88:91], v[72:75], v[84:87], 0
	v_mov_b32_e32 v163, v168
	s_mov_b64 s[20:21], 0x100
	s_mov_b64 s[34:35], 0x8100
	v_mfma_f32_16x16x32_bf16 v[96:99], v[72:75], v[92:95], 0
	s_mov_b64 s[60:61], 0x10100
	s_mov_b64 s[76:77], 0x18100
	v_mfma_f32_16x16x32_bf16 v[72:75], v[72:75], v[100:103], 0
	v_mfma_f32_16x16x32_bf16 v[108:111], v[104:107], v[76:79], 0
	v_mfma_f32_16x16x32_bf16 v[112:115], v[104:107], v[84:87], 0
	v_mfma_f32_16x16x32_bf16 v[116:119], v[104:107], v[92:95], 0
	v_mfma_f32_16x16x32_bf16 v[104:107], v[104:107], v[100:103], 0
	v_mfma_f32_16x16x32_bf16 v[124:127], v[120:123], v[76:79], 0
	v_mfma_f32_16x16x32_bf16 v[128:131], v[120:123], v[84:87], 0
	v_mfma_f32_16x16x32_bf16 v[164:167], v[120:123], v[92:95], 0
	v_mfma_f32_16x16x32_bf16 v[120:123], v[120:123], v[100:103], 0
	v_mfma_f32_16x16x32_bf16 v[76:79], v[202:205], v[76:79], 0
	v_mfma_f32_16x16x32_bf16 v[84:87], v[202:205], v[84:87], 0
	v_mfma_f32_16x16x32_bf16 v[92:95], v[202:205], v[92:95], 0
	v_mfma_f32_16x16x32_bf16 v[100:103], v[202:205], v[100:103], 0
	ds_read_b128 v[202:205], v71
	s_waitcnt lgkmcnt(0)
	v_mfma_f32_16x16x32_bf16 v[80:83], v[206:209], v[202:205], v[80:83]
	v_mfma_f32_16x16x32_bf16 v[88:91], v[206:209], v[210:213], v[88:91]
	v_mfma_f32_16x16x32_bf16 v[96:99], v[206:209], v[214:217], v[96:99]
	v_mfma_f32_16x16x32_bf16 v[72:75], v[206:209], v[218:221], v[72:75]
	ds_read_b128 v[206:209], v69 offset:18432
	s_waitcnt lgkmcnt(0)
	v_mfma_f32_16x16x32_bf16 v[108:111], v[206:209], v[202:205], v[108:111]
	v_mfma_f32_16x16x32_bf16 v[112:115], v[206:209], v[210:213], v[112:115]
	v_mfma_f32_16x16x32_bf16 v[116:119], v[206:209], v[214:217], v[116:119]
	v_mfma_f32_16x16x32_bf16 v[104:107], v[206:209], v[218:221], v[104:107]
	ds_read_b128 v[206:209], v69 offset:20480
	s_waitcnt lgkmcnt(0)
	v_mfma_f32_16x16x32_bf16 v[124:127], v[206:209], v[202:205], v[124:127]
	v_mfma_f32_16x16x32_bf16 v[128:131], v[206:209], v[210:213], v[128:131]
	v_mfma_f32_16x16x32_bf16 v[164:167], v[206:209], v[214:217], v[164:167]
	v_mfma_f32_16x16x32_bf16 v[120:123], v[206:209], v[218:221], v[120:123]
	ds_read_b128 v[206:209], v69 offset:22528
	s_waitcnt vmcnt(0)
	s_waitcnt vmcnt(0) lgkmcnt(0)
	s_barrier
	v_mfma_f32_16x16x32_bf16 v[76:79], v[206:209], v[202:205], v[76:79]
	v_ashrrev_i32_e32 v188, 3, v163
	v_xor_b32_e32 v201, v188, v163
	v_ashrrev_i32_e32 v189, 31, v188
	v_lshlrev_b64 v[188:189], 10, v[188:189]
	v_lshlrev_b32_e32 v201, 4, v201
	v_lshl_add_u64 v[190:191], s[56:57], 0, v[188:189]
	v_and_b32_e32 v202, 0x70, v201
	v_mov_b32_e32 v203, v2
	v_lshlrev_b32_e32 v163, 4, v163
	v_lshl_add_u64 v[190:191], v[190:191], 0, v[202:203]
	v_readfirstlane_b32 s2, v163
	v_add_u32_e32 v201, 0x1000, v163
	v_lshl_add_u64 v[204:205], v[190:191], 0, s[20:21]
	s_mov_b32 m0, s2
	v_readfirstlane_b32 s2, v201
	v_add_u32_e32 v201, 0x2000, v163
	global_load_lds_dwordx4 v[204:205], off
	v_lshl_add_u64 v[204:205], v[190:191], 0, s[34:35]
	s_mov_b32 m0, s2
	v_readfirstlane_b32 s2, v201
	v_add_u32_e32 v201, 0x3000, v163
	v_lshl_add_u64 v[188:189], s[58:59], 0, v[188:189]
	global_load_lds_dwordx4 v[204:205], off
	v_lshl_add_u64 v[204:205], v[190:191], 0, s[60:61]
	s_mov_b32 m0, s2
	v_readfirstlane_b32 s2, v201
	v_add_u32_e32 v201, 0x4000, v163
	global_load_lds_dwordx4 v[204:205], off
	v_lshl_add_u64 v[190:191], v[190:191], 0, s[76:77]
	s_mov_b32 m0, s2
	v_lshl_add_u64 v[188:189], v[188:189], 0, v[202:203]
	v_readfirstlane_b32 s2, v201
	v_add_u32_e32 v201, 0x5000, v163
	global_load_lds_dwordx4 v[190:191], off
	v_lshl_add_u64 v[190:191], v[188:189], 0, s[20:21]
	s_mov_b32 m0, s2
	v_readfirstlane_b32 s2, v201
	v_add_u32_e32 v201, 0x6000, v163
	global_load_lds_dwordx4 v[190:191], off
	v_lshl_add_u64 v[190:191], v[188:189], 0, s[34:35]
	s_mov_b32 m0, s2
	v_readfirstlane_b32 s2, v201
	v_add_u32_e32 v163, 0x7000, v163
	global_load_lds_dwordx4 v[190:191], off
	v_lshl_add_u64 v[190:191], v[188:189], 0, s[60:61]
	s_mov_b32 m0, s2
	v_readfirstlane_b32 s2, v163
	global_load_lds_dwordx4 v[190:191], off
	v_lshl_add_u64 v[188:189], v[188:189], 0, s[76:77]
	s_mov_b32 m0, s2
	v_mfma_f32_16x16x32_bf16 v[84:87], v[206:209], v[210:213], v[84:87]
	global_load_lds_dwordx4 v[188:189], off
	ds_read_b128 v[202:205], v68 offset:49152
	v_mfma_f32_16x16x32_bf16 v[92:95], v[206:209], v[214:217], v[92:95]
	ds_read_b128 v[210:213], v70 offset:34816
	ds_read_b128 v[214:217], v70 offset:36864
	v_mov_b32_e32 v163, v168
	v_mfma_f32_16x16x32_bf16 v[100:103], v[206:209], v[218:221], v[100:103]
	ds_read_b128 v[206:209], v70 offset:32768
	ds_read_b128 v[218:221], v70 offset:38912
	s_mov_b64 s[20:21], 0x180
	s_waitcnt lgkmcnt(0)
	v_mfma_f32_16x16x32_bf16 v[80:83], v[202:205], v[206:209], v[80:83]
	s_mov_b64 s[34:35], 0x8180
	s_mov_b64 s[60:61], 0x10180
	s_mov_b64 s[76:77], 0x18180
	v_mfma_f32_16x16x32_bf16 v[88:91], v[202:205], v[210:213], v[88:91]
	v_mfma_f32_16x16x32_bf16 v[96:99], v[202:205], v[214:217], v[96:99]
	v_mfma_f32_16x16x32_bf16 v[72:75], v[202:205], v[218:221], v[72:75]
	ds_read_b128 v[202:205], v68 offset:51200
	s_waitcnt lgkmcnt(0)
	v_mfma_f32_16x16x32_bf16 v[108:111], v[202:205], v[206:209], v[108:111]
	v_mfma_f32_16x16x32_bf16 v[112:115], v[202:205], v[210:213], v[112:115]
	v_mfma_f32_16x16x32_bf16 v[116:119], v[202:205], v[214:217], v[116:119]
	v_mfma_f32_16x16x32_bf16 v[104:107], v[202:205], v[218:221], v[104:107]
	ds_read_b128 v[202:205], v68 offset:53248
	s_waitcnt lgkmcnt(0)
	v_mfma_f32_16x16x32_bf16 v[124:127], v[202:205], v[206:209], v[124:127]
	v_mfma_f32_16x16x32_bf16 v[128:131], v[202:205], v[210:213], v[128:131]
	v_mfma_f32_16x16x32_bf16 v[164:167], v[202:205], v[214:217], v[164:167]
	v_mfma_f32_16x16x32_bf16 v[120:123], v[202:205], v[218:221], v[120:123]
	ds_read_b128 v[202:205], v68 offset:55296
	s_waitcnt lgkmcnt(0)
	v_mfma_f32_16x16x32_bf16 v[76:79], v[202:205], v[206:209], v[76:79]
	ds_read_b128 v[206:209], v69 offset:49152
	v_mfma_f32_16x16x32_bf16 v[84:87], v[202:205], v[210:213], v[84:87]
	ds_read_b128 v[210:213], v71 offset:34816
	v_mfma_f32_16x16x32_bf16 v[92:95], v[202:205], v[214:217], v[92:95]
	ds_read_b128 v[214:217], v71 offset:36864
	v_mfma_f32_16x16x32_bf16 v[100:103], v[202:205], v[218:221], v[100:103]
	ds_read_b128 v[202:205], v71 offset:32768
	ds_read_b128 v[218:221], v71 offset:38912
	s_waitcnt lgkmcnt(0)
	v_mfma_f32_16x16x32_bf16 v[80:83], v[206:209], v[202:205], v[80:83]
	v_mfma_f32_16x16x32_bf16 v[88:91], v[206:209], v[210:213], v[88:91]
	v_mfma_f32_16x16x32_bf16 v[96:99], v[206:209], v[214:217], v[96:99]
	v_mfma_f32_16x16x32_bf16 v[72:75], v[206:209], v[218:221], v[72:75]
	ds_read_b128 v[206:209], v69 offset:51200
	s_waitcnt lgkmcnt(0)
	v_mfma_f32_16x16x32_bf16 v[108:111], v[206:209], v[202:205], v[108:111]
	v_mfma_f32_16x16x32_bf16 v[112:115], v[206:209], v[210:213], v[112:115]
	v_mfma_f32_16x16x32_bf16 v[116:119], v[206:209], v[214:217], v[116:119]
	v_mfma_f32_16x16x32_bf16 v[104:107], v[206:209], v[218:221], v[104:107]
	ds_read_b128 v[206:209], v69 offset:53248
	s_waitcnt lgkmcnt(0)
	v_mfma_f32_16x16x32_bf16 v[124:127], v[206:209], v[202:205], v[124:127]
	v_mfma_f32_16x16x32_bf16 v[128:131], v[206:209], v[210:213], v[128:131]
	v_mfma_f32_16x16x32_bf16 v[164:167], v[206:209], v[214:217], v[164:167]
	v_mfma_f32_16x16x32_bf16 v[120:123], v[206:209], v[218:221], v[120:123]
	ds_read_b128 v[206:209], v69 offset:55296
	s_waitcnt vmcnt(0)
	s_waitcnt vmcnt(0) lgkmcnt(0)
	s_barrier
	v_mfma_f32_16x16x32_bf16 v[76:79], v[206:209], v[202:205], v[76:79]
	v_ashrrev_i32_e32 v188, 3, v163
	v_xor_b32_e32 v201, v188, v163
	v_ashrrev_i32_e32 v189, 31, v188
	v_lshlrev_b64 v[188:189], 10, v[188:189]
	v_lshlrev_b32_e32 v201, 4, v201
	v_lshlrev_b32_e32 v163, 4, v163
	v_lshl_add_u64 v[190:191], s[56:57], 0, v[188:189]
	v_and_b32_e32 v202, 0x70, v201
	v_mov_b32_e32 v203, v2
	v_add_u32_e32 v201, 0x8000, v163
	v_lshl_add_u64 v[190:191], v[190:191], 0, v[202:203]
	v_readfirstlane_b32 s2, v201
	v_add_u32_e32 v201, 0x9000, v163
	v_lshl_add_u64 v[204:205], v[190:191], 0, s[20:21]
	s_mov_b32 m0, s2
	v_readfirstlane_b32 s2, v201
	v_add_u32_e32 v201, 0xa000, v163
	global_load_lds_dwordx4 v[204:205], off
	v_lshl_add_u64 v[204:205], v[190:191], 0, s[34:35]
	s_mov_b32 m0, s2
	v_readfirstlane_b32 s2, v201
	v_add_u32_e32 v201, 0xb000, v163
	v_lshl_add_u64 v[188:189], s[58:59], 0, v[188:189]
	global_load_lds_dwordx4 v[204:205], off
	v_lshl_add_u64 v[204:205], v[190:191], 0, s[60:61]
	s_mov_b32 m0, s2
	v_readfirstlane_b32 s2, v201
	v_add_u32_e32 v201, 0xc000, v163
	global_load_lds_dwordx4 v[204:205], off
	v_lshl_add_u64 v[190:191], v[190:191], 0, s[76:77]
	s_mov_b32 m0, s2
	v_lshl_add_u64 v[188:189], v[188:189], 0, v[202:203]
	v_readfirstlane_b32 s2, v201
	v_add_u32_e32 v201, 0xd000, v163
	global_load_lds_dwordx4 v[190:191], off
	v_lshl_add_u64 v[190:191], v[188:189], 0, s[20:21]
	s_mov_b32 m0, s2
	v_readfirstlane_b32 s2, v201
	v_add_u32_e32 v201, 0xe000, v163
	global_load_lds_dwordx4 v[190:191], off
	v_lshl_add_u64 v[190:191], v[188:189], 0, s[34:35]
	s_mov_b32 m0, s2
	v_readfirstlane_b32 s2, v201
	v_add_u32_e32 v163, 0xf000, v163
	global_load_lds_dwordx4 v[190:191], off
	v_lshl_add_u64 v[190:191], v[188:189], 0, s[60:61]
	s_mov_b32 m0, s2
	v_readfirstlane_b32 s2, v163
	global_load_lds_dwordx4 v[190:191], off
	v_lshl_add_u64 v[188:189], v[188:189], 0, s[76:77]
	s_mov_b32 m0, s2
	v_mfma_f32_16x16x32_bf16 v[84:87], v[206:209], v[210:213], v[84:87]
	global_load_lds_dwordx4 v[188:189], off
	ds_read_b128 v[202:205], v68 offset:16384
	v_mfma_f32_16x16x32_bf16 v[92:95], v[206:209], v[214:217], v[92:95]
	ds_read_b128 v[210:213], v70 offset:2048
	ds_read_b128 v[214:217], v70 offset:4096
	v_mov_b32_e32 v163, v168
	v_mfma_f32_16x16x32_bf16 v[100:103], v[206:209], v[218:221], v[100:103]
	ds_read_b128 v[206:209], v70
	ds_read_b128 v[218:221], v70 offset:6144
	s_mov_b64 s[20:21], 0x200
	s_waitcnt lgkmcnt(0)
	v_mfma_f32_16x16x32_bf16 v[80:83], v[202:205], v[206:209], v[80:83]
	s_mov_b64 s[34:35], 0x8200
	s_mov_b64 s[60:61], 0x10200
	s_mov_b64 s[76:77], 0x18200
	v_mfma_f32_16x16x32_bf16 v[88:91], v[202:205], v[210:213], v[88:91]
	v_mfma_f32_16x16x32_bf16 v[96:99], v[202:205], v[214:217], v[96:99]
	v_mfma_f32_16x16x32_bf16 v[72:75], v[202:205], v[218:221], v[72:75]
	ds_read_b128 v[202:205], v68 offset:18432
	s_waitcnt lgkmcnt(0)
	v_mfma_f32_16x16x32_bf16 v[108:111], v[202:205], v[206:209], v[108:111]
	v_mfma_f32_16x16x32_bf16 v[112:115], v[202:205], v[210:213], v[112:115]
	v_mfma_f32_16x16x32_bf16 v[116:119], v[202:205], v[214:217], v[116:119]
	v_mfma_f32_16x16x32_bf16 v[104:107], v[202:205], v[218:221], v[104:107]
	ds_read_b128 v[202:205], v68 offset:20480
	s_waitcnt lgkmcnt(0)
	v_mfma_f32_16x16x32_bf16 v[124:127], v[202:205], v[206:209], v[124:127]
	v_mfma_f32_16x16x32_bf16 v[128:131], v[202:205], v[210:213], v[128:131]
	v_mfma_f32_16x16x32_bf16 v[164:167], v[202:205], v[214:217], v[164:167]
	v_mfma_f32_16x16x32_bf16 v[120:123], v[202:205], v[218:221], v[120:123]
	ds_read_b128 v[202:205], v68 offset:22528
	s_waitcnt lgkmcnt(0)
	v_mfma_f32_16x16x32_bf16 v[76:79], v[202:205], v[206:209], v[76:79]
	ds_read_b128 v[206:209], v69 offset:16384
	v_mfma_f32_16x16x32_bf16 v[84:87], v[202:205], v[210:213], v[84:87]
	ds_read_b128 v[210:213], v71 offset:2048
	v_mfma_f32_16x16x32_bf16 v[92:95], v[202:205], v[214:217], v[92:95]
	ds_read_b128 v[214:217], v71 offset:4096
	v_mfma_f32_16x16x32_bf16 v[100:103], v[202:205], v[218:221], v[100:103]
	ds_read_b128 v[202:205], v71
	ds_read_b128 v[218:221], v71 offset:6144
	s_waitcnt lgkmcnt(0)
	v_mfma_f32_16x16x32_bf16 v[80:83], v[206:209], v[202:205], v[80:83]
	v_mfma_f32_16x16x32_bf16 v[88:91], v[206:209], v[210:213], v[88:91]
	v_mfma_f32_16x16x32_bf16 v[96:99], v[206:209], v[214:217], v[96:99]
	v_mfma_f32_16x16x32_bf16 v[72:75], v[206:209], v[218:221], v[72:75]
	ds_read_b128 v[206:209], v69 offset:18432
	s_waitcnt lgkmcnt(0)
	v_mfma_f32_16x16x32_bf16 v[108:111], v[206:209], v[202:205], v[108:111]
	v_mfma_f32_16x16x32_bf16 v[112:115], v[206:209], v[210:213], v[112:115]
	v_mfma_f32_16x16x32_bf16 v[116:119], v[206:209], v[214:217], v[116:119]
	v_mfma_f32_16x16x32_bf16 v[104:107], v[206:209], v[218:221], v[104:107]
	ds_read_b128 v[206:209], v69 offset:20480
	s_waitcnt lgkmcnt(0)
	v_mfma_f32_16x16x32_bf16 v[124:127], v[206:209], v[202:205], v[124:127]
	v_mfma_f32_16x16x32_bf16 v[128:131], v[206:209], v[210:213], v[128:131]
	v_mfma_f32_16x16x32_bf16 v[164:167], v[206:209], v[214:217], v[164:167]
	v_mfma_f32_16x16x32_bf16 v[120:123], v[206:209], v[218:221], v[120:123]
	ds_read_b128 v[206:209], v69 offset:22528
	s_waitcnt vmcnt(0)
	s_waitcnt vmcnt(0) lgkmcnt(0)
	s_barrier
	v_mfma_f32_16x16x32_bf16 v[76:79], v[206:209], v[202:205], v[76:79]
	v_ashrrev_i32_e32 v188, 3, v163
	v_xor_b32_e32 v201, v188, v163
	v_ashrrev_i32_e32 v189, 31, v188
	v_lshlrev_b64 v[188:189], 10, v[188:189]
	v_lshlrev_b32_e32 v201, 4, v201
	v_lshl_add_u64 v[190:191], s[56:57], 0, v[188:189]
	v_and_b32_e32 v202, 0x70, v201
	v_mov_b32_e32 v203, v2
	v_lshlrev_b32_e32 v163, 4, v163
	v_lshl_add_u64 v[190:191], v[190:191], 0, v[202:203]
	v_readfirstlane_b32 s2, v163
	v_add_u32_e32 v201, 0x1000, v163
	v_lshl_add_u64 v[204:205], v[190:191], 0, s[20:21]
	s_mov_b32 m0, s2
	v_readfirstlane_b32 s2, v201
	v_add_u32_e32 v201, 0x2000, v163
	global_load_lds_dwordx4 v[204:205], off
	v_lshl_add_u64 v[204:205], v[190:191], 0, s[34:35]
	s_mov_b32 m0, s2
	v_readfirstlane_b32 s2, v201
	v_add_u32_e32 v201, 0x3000, v163
	v_lshl_add_u64 v[188:189], s[58:59], 0, v[188:189]
	global_load_lds_dwordx4 v[204:205], off
	v_lshl_add_u64 v[204:205], v[190:191], 0, s[60:61]
	s_mov_b32 m0, s2
	v_readfirstlane_b32 s2, v201
	v_add_u32_e32 v201, 0x4000, v163
	global_load_lds_dwordx4 v[204:205], off
	v_lshl_add_u64 v[190:191], v[190:191], 0, s[76:77]
	s_mov_b32 m0, s2
	v_lshl_add_u64 v[188:189], v[188:189], 0, v[202:203]
	v_readfirstlane_b32 s2, v201
	v_add_u32_e32 v201, 0x5000, v163
	global_load_lds_dwordx4 v[190:191], off
	v_lshl_add_u64 v[190:191], v[188:189], 0, s[20:21]
	s_mov_b32 m0, s2
	v_readfirstlane_b32 s2, v201
	v_add_u32_e32 v201, 0x6000, v163
	global_load_lds_dwordx4 v[190:191], off
	v_lshl_add_u64 v[190:191], v[188:189], 0, s[34:35]
	s_mov_b32 m0, s2
	v_readfirstlane_b32 s2, v201
	v_add_u32_e32 v163, 0x7000, v163
	global_load_lds_dwordx4 v[190:191], off
	v_lshl_add_u64 v[190:191], v[188:189], 0, s[60:61]
	s_mov_b32 m0, s2
	v_readfirstlane_b32 s2, v163
	global_load_lds_dwordx4 v[190:191], off
	v_lshl_add_u64 v[188:189], v[188:189], 0, s[76:77]
	s_mov_b32 m0, s2
	v_mfma_f32_16x16x32_bf16 v[84:87], v[206:209], v[210:213], v[84:87]
	global_load_lds_dwordx4 v[188:189], off
	ds_read_b128 v[202:205], v68 offset:49152
	v_mfma_f32_16x16x32_bf16 v[92:95], v[206:209], v[214:217], v[92:95]
	ds_read_b128 v[210:213], v70 offset:34816
	ds_read_b128 v[214:217], v70 offset:36864
	v_mov_b32_e32 v163, v168
	v_mfma_f32_16x16x32_bf16 v[100:103], v[206:209], v[218:221], v[100:103]
	ds_read_b128 v[206:209], v70 offset:32768
	ds_read_b128 v[218:221], v70 offset:38912
	s_mov_b64 s[20:21], 0x280
	s_waitcnt lgkmcnt(0)
	v_mfma_f32_16x16x32_bf16 v[80:83], v[202:205], v[206:209], v[80:83]
	s_mov_b64 s[34:35], 0x8280
	s_mov_b64 s[60:61], 0x10280
	s_mov_b64 s[76:77], 0x18280
	v_mfma_f32_16x16x32_bf16 v[88:91], v[202:205], v[210:213], v[88:91]
	v_mfma_f32_16x16x32_bf16 v[96:99], v[202:205], v[214:217], v[96:99]
	v_mfma_f32_16x16x32_bf16 v[72:75], v[202:205], v[218:221], v[72:75]
	ds_read_b128 v[202:205], v68 offset:51200
	s_waitcnt lgkmcnt(0)
	v_mfma_f32_16x16x32_bf16 v[108:111], v[202:205], v[206:209], v[108:111]
	v_mfma_f32_16x16x32_bf16 v[112:115], v[202:205], v[210:213], v[112:115]
	v_mfma_f32_16x16x32_bf16 v[116:119], v[202:205], v[214:217], v[116:119]
	v_mfma_f32_16x16x32_bf16 v[104:107], v[202:205], v[218:221], v[104:107]
	ds_read_b128 v[202:205], v68 offset:53248
	s_waitcnt lgkmcnt(0)
	v_mfma_f32_16x16x32_bf16 v[124:127], v[202:205], v[206:209], v[124:127]
	v_mfma_f32_16x16x32_bf16 v[128:131], v[202:205], v[210:213], v[128:131]
	v_mfma_f32_16x16x32_bf16 v[164:167], v[202:205], v[214:217], v[164:167]
	v_mfma_f32_16x16x32_bf16 v[120:123], v[202:205], v[218:221], v[120:123]
	ds_read_b128 v[202:205], v68 offset:55296
	s_waitcnt lgkmcnt(0)
	v_mfma_f32_16x16x32_bf16 v[76:79], v[202:205], v[206:209], v[76:79]
	ds_read_b128 v[206:209], v69 offset:49152
	v_mfma_f32_16x16x32_bf16 v[84:87], v[202:205], v[210:213], v[84:87]
	ds_read_b128 v[210:213], v71 offset:34816
	v_mfma_f32_16x16x32_bf16 v[92:95], v[202:205], v[214:217], v[92:95]
	ds_read_b128 v[214:217], v71 offset:36864
	v_mfma_f32_16x16x32_bf16 v[100:103], v[202:205], v[218:221], v[100:103]
	ds_read_b128 v[202:205], v71 offset:32768
	ds_read_b128 v[218:221], v71 offset:38912
	s_waitcnt lgkmcnt(0)
	v_mfma_f32_16x16x32_bf16 v[80:83], v[206:209], v[202:205], v[80:83]
	v_mfma_f32_16x16x32_bf16 v[88:91], v[206:209], v[210:213], v[88:91]
	v_mfma_f32_16x16x32_bf16 v[96:99], v[206:209], v[214:217], v[96:99]
	v_mfma_f32_16x16x32_bf16 v[72:75], v[206:209], v[218:221], v[72:75]
	ds_read_b128 v[206:209], v69 offset:51200
	s_waitcnt lgkmcnt(0)
	v_mfma_f32_16x16x32_bf16 v[108:111], v[206:209], v[202:205], v[108:111]
	v_mfma_f32_16x16x32_bf16 v[112:115], v[206:209], v[210:213], v[112:115]
	v_mfma_f32_16x16x32_bf16 v[116:119], v[206:209], v[214:217], v[116:119]
	v_mfma_f32_16x16x32_bf16 v[104:107], v[206:209], v[218:221], v[104:107]
	ds_read_b128 v[206:209], v69 offset:53248
	s_waitcnt lgkmcnt(0)
	v_mfma_f32_16x16x32_bf16 v[124:127], v[206:209], v[202:205], v[124:127]
	v_mfma_f32_16x16x32_bf16 v[128:131], v[206:209], v[210:213], v[128:131]
	v_mfma_f32_16x16x32_bf16 v[164:167], v[206:209], v[214:217], v[164:167]
	v_mfma_f32_16x16x32_bf16 v[120:123], v[206:209], v[218:221], v[120:123]
	ds_read_b128 v[206:209], v69 offset:55296
	s_waitcnt vmcnt(0)
	s_waitcnt vmcnt(0) lgkmcnt(0)
	s_barrier
	v_mfma_f32_16x16x32_bf16 v[76:79], v[206:209], v[202:205], v[76:79]
	v_ashrrev_i32_e32 v188, 3, v163
	v_xor_b32_e32 v201, v188, v163
	v_ashrrev_i32_e32 v189, 31, v188
	v_lshlrev_b64 v[188:189], 10, v[188:189]
	v_lshlrev_b32_e32 v201, 4, v201
	v_lshlrev_b32_e32 v163, 4, v163
	v_lshl_add_u64 v[190:191], s[56:57], 0, v[188:189]
	v_and_b32_e32 v202, 0x70, v201
	v_mov_b32_e32 v203, v2
	v_add_u32_e32 v201, 0x8000, v163
	v_lshl_add_u64 v[190:191], v[190:191], 0, v[202:203]
	v_readfirstlane_b32 s2, v201
	v_add_u32_e32 v201, 0x9000, v163
	v_lshl_add_u64 v[204:205], v[190:191], 0, s[20:21]
	s_mov_b32 m0, s2
	v_readfirstlane_b32 s2, v201
	v_add_u32_e32 v201, 0xa000, v163
	global_load_lds_dwordx4 v[204:205], off
	v_lshl_add_u64 v[204:205], v[190:191], 0, s[34:35]
	s_mov_b32 m0, s2
	v_readfirstlane_b32 s2, v201
	v_add_u32_e32 v201, 0xb000, v163
	v_lshl_add_u64 v[188:189], s[58:59], 0, v[188:189]
	global_load_lds_dwordx4 v[204:205], off
	v_lshl_add_u64 v[204:205], v[190:191], 0, s[60:61]
	s_mov_b32 m0, s2
	v_readfirstlane_b32 s2, v201
	v_add_u32_e32 v201, 0xc000, v163
	global_load_lds_dwordx4 v[204:205], off
	v_lshl_add_u64 v[190:191], v[190:191], 0, s[76:77]
	s_mov_b32 m0, s2
	v_lshl_add_u64 v[188:189], v[188:189], 0, v[202:203]
	v_readfirstlane_b32 s2, v201
	v_add_u32_e32 v201, 0xd000, v163
	global_load_lds_dwordx4 v[190:191], off
	v_lshl_add_u64 v[190:191], v[188:189], 0, s[20:21]
	s_mov_b32 m0, s2
	v_readfirstlane_b32 s2, v201
	v_add_u32_e32 v201, 0xe000, v163
	global_load_lds_dwordx4 v[190:191], off
	v_lshl_add_u64 v[190:191], v[188:189], 0, s[34:35]
	s_mov_b32 m0, s2
	v_readfirstlane_b32 s2, v201
	v_add_u32_e32 v163, 0xf000, v163
	global_load_lds_dwordx4 v[190:191], off
	v_lshl_add_u64 v[190:191], v[188:189], 0, s[60:61]
	s_mov_b32 m0, s2
	v_readfirstlane_b32 s2, v163
	global_load_lds_dwordx4 v[190:191], off
	v_lshl_add_u64 v[188:189], v[188:189], 0, s[76:77]
	s_mov_b32 m0, s2
	v_mfma_f32_16x16x32_bf16 v[84:87], v[206:209], v[210:213], v[84:87]
	global_load_lds_dwordx4 v[188:189], off
	ds_read_b128 v[202:205], v68 offset:16384
	v_mfma_f32_16x16x32_bf16 v[92:95], v[206:209], v[214:217], v[92:95]
	ds_read_b128 v[210:213], v70 offset:2048
	ds_read_b128 v[214:217], v70 offset:4096
	v_mov_b32_e32 v163, v168
	v_mfma_f32_16x16x32_bf16 v[100:103], v[206:209], v[218:221], v[100:103]
	ds_read_b128 v[206:209], v70
	ds_read_b128 v[218:221], v70 offset:6144
	s_mov_b64 s[20:21], 0x300
	s_waitcnt lgkmcnt(0)
	v_mfma_f32_16x16x32_bf16 v[80:83], v[202:205], v[206:209], v[80:83]
	s_mov_b64 s[34:35], 0x8300
	s_mov_b64 s[60:61], 0x10300
	s_mov_b64 s[76:77], 0x18300
	v_mfma_f32_16x16x32_bf16 v[88:91], v[202:205], v[210:213], v[88:91]
	v_mfma_f32_16x16x32_bf16 v[96:99], v[202:205], v[214:217], v[96:99]
	v_mfma_f32_16x16x32_bf16 v[72:75], v[202:205], v[218:221], v[72:75]
	ds_read_b128 v[202:205], v68 offset:18432
	s_waitcnt lgkmcnt(0)
	v_mfma_f32_16x16x32_bf16 v[108:111], v[202:205], v[206:209], v[108:111]
	v_mfma_f32_16x16x32_bf16 v[112:115], v[202:205], v[210:213], v[112:115]
	v_mfma_f32_16x16x32_bf16 v[116:119], v[202:205], v[214:217], v[116:119]
	v_mfma_f32_16x16x32_bf16 v[104:107], v[202:205], v[218:221], v[104:107]
	ds_read_b128 v[202:205], v68 offset:20480
	s_waitcnt lgkmcnt(0)
	v_mfma_f32_16x16x32_bf16 v[124:127], v[202:205], v[206:209], v[124:127]
	v_mfma_f32_16x16x32_bf16 v[128:131], v[202:205], v[210:213], v[128:131]
	v_mfma_f32_16x16x32_bf16 v[164:167], v[202:205], v[214:217], v[164:167]
	v_mfma_f32_16x16x32_bf16 v[120:123], v[202:205], v[218:221], v[120:123]
	ds_read_b128 v[202:205], v68 offset:22528
	s_waitcnt lgkmcnt(0)
	v_mfma_f32_16x16x32_bf16 v[76:79], v[202:205], v[206:209], v[76:79]
	ds_read_b128 v[206:209], v69 offset:16384
	v_mfma_f32_16x16x32_bf16 v[84:87], v[202:205], v[210:213], v[84:87]
	ds_read_b128 v[210:213], v71 offset:2048
	v_mfma_f32_16x16x32_bf16 v[92:95], v[202:205], v[214:217], v[92:95]
	ds_read_b128 v[214:217], v71 offset:4096
	v_mfma_f32_16x16x32_bf16 v[100:103], v[202:205], v[218:221], v[100:103]
	ds_read_b128 v[202:205], v71
	ds_read_b128 v[218:221], v71 offset:6144
	s_waitcnt lgkmcnt(0)
	v_mfma_f32_16x16x32_bf16 v[80:83], v[206:209], v[202:205], v[80:83]
	v_mfma_f32_16x16x32_bf16 v[88:91], v[206:209], v[210:213], v[88:91]
	v_mfma_f32_16x16x32_bf16 v[96:99], v[206:209], v[214:217], v[96:99]
	v_mfma_f32_16x16x32_bf16 v[72:75], v[206:209], v[218:221], v[72:75]
	ds_read_b128 v[206:209], v69 offset:18432
	s_waitcnt lgkmcnt(0)
	v_mfma_f32_16x16x32_bf16 v[108:111], v[206:209], v[202:205], v[108:111]
	v_mfma_f32_16x16x32_bf16 v[112:115], v[206:209], v[210:213], v[112:115]
	v_mfma_f32_16x16x32_bf16 v[116:119], v[206:209], v[214:217], v[116:119]
	v_mfma_f32_16x16x32_bf16 v[104:107], v[206:209], v[218:221], v[104:107]
	ds_read_b128 v[206:209], v69 offset:20480
	s_waitcnt lgkmcnt(0)
	v_mfma_f32_16x16x32_bf16 v[124:127], v[206:209], v[202:205], v[124:127]
	v_mfma_f32_16x16x32_bf16 v[128:131], v[206:209], v[210:213], v[128:131]
	v_mfma_f32_16x16x32_bf16 v[164:167], v[206:209], v[214:217], v[164:167]
	v_mfma_f32_16x16x32_bf16 v[120:123], v[206:209], v[218:221], v[120:123]
	ds_read_b128 v[206:209], v69 offset:22528
	s_waitcnt vmcnt(0)
	s_waitcnt vmcnt(0) lgkmcnt(0)
	s_barrier
	v_mfma_f32_16x16x32_bf16 v[76:79], v[206:209], v[202:205], v[76:79]
	v_ashrrev_i32_e32 v188, 3, v163
	v_xor_b32_e32 v201, v188, v163
	v_ashrrev_i32_e32 v189, 31, v188
	v_lshlrev_b64 v[188:189], 10, v[188:189]
	v_lshlrev_b32_e32 v201, 4, v201
	v_lshl_add_u64 v[190:191], s[56:57], 0, v[188:189]
	v_and_b32_e32 v202, 0x70, v201
	v_mov_b32_e32 v203, v2
	v_lshlrev_b32_e32 v163, 4, v163
	v_lshl_add_u64 v[190:191], v[190:191], 0, v[202:203]
	v_readfirstlane_b32 s2, v163
	v_add_u32_e32 v201, 0x1000, v163
	v_lshl_add_u64 v[204:205], v[190:191], 0, s[20:21]
	s_mov_b32 m0, s2
	v_readfirstlane_b32 s2, v201
	v_add_u32_e32 v201, 0x2000, v163
	global_load_lds_dwordx4 v[204:205], off
	v_lshl_add_u64 v[204:205], v[190:191], 0, s[34:35]
	s_mov_b32 m0, s2
	v_readfirstlane_b32 s2, v201
	v_add_u32_e32 v201, 0x3000, v163
	v_lshl_add_u64 v[188:189], s[58:59], 0, v[188:189]
	global_load_lds_dwordx4 v[204:205], off
	v_lshl_add_u64 v[204:205], v[190:191], 0, s[60:61]
	s_mov_b32 m0, s2
	v_readfirstlane_b32 s2, v201
	v_add_u32_e32 v201, 0x4000, v163
	global_load_lds_dwordx4 v[204:205], off
	v_lshl_add_u64 v[190:191], v[190:191], 0, s[76:77]
	s_mov_b32 m0, s2
	v_lshl_add_u64 v[188:189], v[188:189], 0, v[202:203]
	v_readfirstlane_b32 s2, v201
	v_add_u32_e32 v201, 0x5000, v163
	global_load_lds_dwordx4 v[190:191], off
	v_lshl_add_u64 v[190:191], v[188:189], 0, s[20:21]
	s_mov_b32 m0, s2
	v_readfirstlane_b32 s2, v201
	v_add_u32_e32 v201, 0x6000, v163
	global_load_lds_dwordx4 v[190:191], off
	v_lshl_add_u64 v[190:191], v[188:189], 0, s[34:35]
	s_mov_b32 m0, s2
	v_readfirstlane_b32 s2, v201
	v_add_u32_e32 v163, 0x7000, v163
	global_load_lds_dwordx4 v[190:191], off
	v_lshl_add_u64 v[190:191], v[188:189], 0, s[60:61]
	s_mov_b32 m0, s2
	v_readfirstlane_b32 s2, v163
	global_load_lds_dwordx4 v[190:191], off
	v_lshl_add_u64 v[188:189], v[188:189], 0, s[76:77]
	s_mov_b32 m0, s2
	v_mfma_f32_16x16x32_bf16 v[84:87], v[206:209], v[210:213], v[84:87]
	global_load_lds_dwordx4 v[188:189], off
	ds_read_b128 v[202:205], v68 offset:49152
	v_mfma_f32_16x16x32_bf16 v[92:95], v[206:209], v[214:217], v[92:95]
	ds_read_b128 v[210:213], v70 offset:34816
	ds_read_b128 v[214:217], v70 offset:36864
	v_mov_b32_e32 v163, v168
	v_mfma_f32_16x16x32_bf16 v[100:103], v[206:209], v[218:221], v[100:103]
	ds_read_b128 v[206:209], v70 offset:32768
	ds_read_b128 v[218:221], v70 offset:38912
	s_mov_b64 s[20:21], 0x380
	s_waitcnt lgkmcnt(0)
	v_mfma_f32_16x16x32_bf16 v[80:83], v[202:205], v[206:209], v[80:83]
	s_mov_b64 s[34:35], 0x8380
	v_mfma_f32_16x16x32_bf16 v[88:91], v[202:205], v[210:213], v[88:91]
	v_mfma_f32_16x16x32_bf16 v[96:99], v[202:205], v[214:217], v[96:99]
	v_mfma_f32_16x16x32_bf16 v[72:75], v[202:205], v[218:221], v[72:75]
	ds_read_b128 v[202:205], v68 offset:51200
	s_waitcnt lgkmcnt(0)
	v_mfma_f32_16x16x32_bf16 v[108:111], v[202:205], v[206:209], v[108:111]
	v_mfma_f32_16x16x32_bf16 v[112:115], v[202:205], v[210:213], v[112:115]
	v_mfma_f32_16x16x32_bf16 v[116:119], v[202:205], v[214:217], v[116:119]
	v_mfma_f32_16x16x32_bf16 v[104:107], v[202:205], v[218:221], v[104:107]
	ds_read_b128 v[202:205], v68 offset:53248
	s_waitcnt lgkmcnt(0)
	v_mfma_f32_16x16x32_bf16 v[124:127], v[202:205], v[206:209], v[124:127]
	v_mfma_f32_16x16x32_bf16 v[128:131], v[202:205], v[210:213], v[128:131]
	v_mfma_f32_16x16x32_bf16 v[164:167], v[202:205], v[214:217], v[164:167]
	v_mfma_f32_16x16x32_bf16 v[120:123], v[202:205], v[218:221], v[120:123]
	ds_read_b128 v[202:205], v68 offset:55296
	s_waitcnt lgkmcnt(0)
	v_mfma_f32_16x16x32_bf16 v[76:79], v[202:205], v[206:209], v[76:79]
	ds_read_b128 v[206:209], v69 offset:49152
	v_mfma_f32_16x16x32_bf16 v[84:87], v[202:205], v[210:213], v[84:87]
	ds_read_b128 v[210:213], v71 offset:34816
	v_mfma_f32_16x16x32_bf16 v[92:95], v[202:205], v[214:217], v[92:95]
	ds_read_b128 v[214:217], v71 offset:36864
	v_mfma_f32_16x16x32_bf16 v[100:103], v[202:205], v[218:221], v[100:103]
	ds_read_b128 v[202:205], v71 offset:32768
	ds_read_b128 v[218:221], v71 offset:38912
	s_waitcnt lgkmcnt(0)
	v_mfma_f32_16x16x32_bf16 v[80:83], v[206:209], v[202:205], v[80:83]
	v_mfma_f32_16x16x32_bf16 v[88:91], v[206:209], v[210:213], v[88:91]
	v_mfma_f32_16x16x32_bf16 v[96:99], v[206:209], v[214:217], v[96:99]
	v_mfma_f32_16x16x32_bf16 v[72:75], v[206:209], v[218:221], v[72:75]
	ds_read_b128 v[206:209], v69 offset:51200
	s_waitcnt lgkmcnt(0)
	v_mfma_f32_16x16x32_bf16 v[108:111], v[206:209], v[202:205], v[108:111]
	v_mfma_f32_16x16x32_bf16 v[112:115], v[206:209], v[210:213], v[112:115]
	v_mfma_f32_16x16x32_bf16 v[116:119], v[206:209], v[214:217], v[116:119]
	v_mfma_f32_16x16x32_bf16 v[104:107], v[206:209], v[218:221], v[104:107]
	ds_read_b128 v[206:209], v69 offset:53248
	s_waitcnt lgkmcnt(0)
	v_mfma_f32_16x16x32_bf16 v[124:127], v[206:209], v[202:205], v[124:127]
	v_mfma_f32_16x16x32_bf16 v[128:131], v[206:209], v[210:213], v[128:131]
	v_mfma_f32_16x16x32_bf16 v[164:167], v[206:209], v[214:217], v[164:167]
	v_mfma_f32_16x16x32_bf16 v[120:123], v[206:209], v[218:221], v[120:123]
	ds_read_b128 v[206:209], v69 offset:55296
	s_waitcnt vmcnt(0)
	s_waitcnt vmcnt(0) lgkmcnt(0)
	s_barrier
	v_mfma_f32_16x16x32_bf16 v[76:79], v[206:209], v[202:205], v[76:79]
	v_ashrrev_i32_e32 v188, 3, v163
	v_xor_b32_e32 v201, v188, v163
	v_ashrrev_i32_e32 v189, 31, v188
	v_lshlrev_b64 v[188:189], 10, v[188:189]
	v_lshlrev_b32_e32 v201, 4, v201
	v_lshlrev_b32_e32 v163, 4, v163
	v_lshl_add_u64 v[190:191], s[56:57], 0, v[188:189]
	v_and_b32_e32 v202, 0x70, v201
	v_mov_b32_e32 v203, v2
	v_add_u32_e32 v201, 0x8000, v163
	v_lshl_add_u64 v[190:191], v[190:191], 0, v[202:203]
	v_readfirstlane_b32 s2, v201
	v_add_u32_e32 v201, 0x9000, v163
	v_lshl_add_u64 v[204:205], v[190:191], 0, s[20:21]
	s_mov_b32 m0, s2
	v_readfirstlane_b32 s2, v201
	v_add_u32_e32 v201, 0xa000, v163
	global_load_lds_dwordx4 v[204:205], off
	v_lshl_add_u64 v[204:205], v[190:191], 0, s[34:35]
	s_mov_b32 m0, s2
	s_mov_b64 s[56:57], 0x10380
	v_readfirstlane_b32 s2, v201
	v_add_u32_e32 v201, 0xb000, v163
	v_lshl_add_u64 v[188:189], s[58:59], 0, v[188:189]
	global_load_lds_dwordx4 v[204:205], off
	v_lshl_add_u64 v[204:205], v[190:191], 0, s[56:57]
	s_mov_b32 m0, s2
	s_mov_b64 s[58:59], 0x18380
	v_readfirstlane_b32 s2, v201
	v_add_u32_e32 v201, 0xc000, v163
	global_load_lds_dwordx4 v[204:205], off
	v_lshl_add_u64 v[190:191], v[190:191], 0, s[58:59]
	s_mov_b32 m0, s2
	v_lshl_add_u64 v[188:189], v[188:189], 0, v[202:203]
	v_readfirstlane_b32 s2, v201
	v_add_u32_e32 v201, 0xd000, v163
	global_load_lds_dwordx4 v[190:191], off
	v_lshl_add_u64 v[190:191], v[188:189], 0, s[20:21]
	s_mov_b32 m0, s2
	v_readfirstlane_b32 s2, v201
	v_add_u32_e32 v201, 0xe000, v163
	global_load_lds_dwordx4 v[190:191], off
	v_lshl_add_u64 v[190:191], v[188:189], 0, s[34:35]
	s_mov_b32 m0, s2
	v_readfirstlane_b32 s2, v201
	v_add_u32_e32 v163, 0xf000, v163
	global_load_lds_dwordx4 v[190:191], off
	v_lshl_add_u64 v[190:191], v[188:189], 0, s[56:57]
	s_mov_b32 m0, s2
	v_readfirstlane_b32 s2, v163
	global_load_lds_dwordx4 v[190:191], off
	v_lshl_add_u64 v[188:189], v[188:189], 0, s[58:59]
	s_mov_b32 m0, s2
	v_mfma_f32_16x16x32_bf16 v[84:87], v[206:209], v[210:213], v[84:87]
	global_load_lds_dwordx4 v[188:189], off
	ds_read_b128 v[202:205], v68 offset:16384
	v_mfma_f32_16x16x32_bf16 v[92:95], v[206:209], v[214:217], v[92:95]
	ds_read_b128 v[210:213], v70 offset:2048
	ds_read_b128 v[214:217], v70 offset:4096
	v_mfma_f32_16x16x32_bf16 v[100:103], v[206:209], v[218:221], v[100:103]
	ds_read_b128 v[206:209], v70
	ds_read_b128 v[218:221], v70 offset:6144
	s_waitcnt lgkmcnt(0)
	v_mfma_f32_16x16x32_bf16 v[80:83], v[202:205], v[206:209], v[80:83]
	v_mfma_f32_16x16x32_bf16 v[88:91], v[202:205], v[210:213], v[88:91]
	v_mfma_f32_16x16x32_bf16 v[96:99], v[202:205], v[214:217], v[96:99]
	v_mfma_f32_16x16x32_bf16 v[72:75], v[202:205], v[218:221], v[72:75]
	ds_read_b128 v[202:205], v68 offset:18432
	s_waitcnt lgkmcnt(0)
	v_mfma_f32_16x16x32_bf16 v[108:111], v[202:205], v[206:209], v[108:111]
	v_mfma_f32_16x16x32_bf16 v[112:115], v[202:205], v[210:213], v[112:115]
	v_mfma_f32_16x16x32_bf16 v[116:119], v[202:205], v[214:217], v[116:119]
	v_mfma_f32_16x16x32_bf16 v[104:107], v[202:205], v[218:221], v[104:107]
	ds_read_b128 v[202:205], v68 offset:20480
	s_waitcnt lgkmcnt(0)
	v_mfma_f32_16x16x32_bf16 v[124:127], v[202:205], v[206:209], v[124:127]
	v_mfma_f32_16x16x32_bf16 v[128:131], v[202:205], v[210:213], v[128:131]
	v_mfma_f32_16x16x32_bf16 v[164:167], v[202:205], v[214:217], v[164:167]
	v_mfma_f32_16x16x32_bf16 v[120:123], v[202:205], v[218:221], v[120:123]
	ds_read_b128 v[202:205], v68 offset:22528
	s_waitcnt lgkmcnt(0)
	v_mfma_f32_16x16x32_bf16 v[76:79], v[202:205], v[206:209], v[76:79]
	ds_read_b128 v[206:209], v69 offset:16384
	v_mfma_f32_16x16x32_bf16 v[84:87], v[202:205], v[210:213], v[84:87]
	ds_read_b128 v[210:213], v71 offset:2048
	v_mfma_f32_16x16x32_bf16 v[92:95], v[202:205], v[214:217], v[92:95]
	ds_read_b128 v[214:217], v71 offset:4096
	v_mfma_f32_16x16x32_bf16 v[100:103], v[202:205], v[218:221], v[100:103]
	ds_read_b128 v[202:205], v71
	ds_read_b128 v[218:221], v71 offset:6144
	s_waitcnt lgkmcnt(0)
	v_mfma_f32_16x16x32_bf16 v[80:83], v[206:209], v[202:205], v[80:83]
	v_mfma_f32_16x16x32_bf16 v[88:91], v[206:209], v[210:213], v[88:91]
	v_mfma_f32_16x16x32_bf16 v[96:99], v[206:209], v[214:217], v[96:99]
	v_mfma_f32_16x16x32_bf16 v[72:75], v[206:209], v[218:221], v[72:75]
	ds_read_b128 v[206:209], v69 offset:18432
	s_waitcnt lgkmcnt(0)
	v_mfma_f32_16x16x32_bf16 v[108:111], v[206:209], v[202:205], v[108:111]
	v_mfma_f32_16x16x32_bf16 v[112:115], v[206:209], v[210:213], v[112:115]
	v_mfma_f32_16x16x32_bf16 v[116:119], v[206:209], v[214:217], v[116:119]
	v_mfma_f32_16x16x32_bf16 v[104:107], v[206:209], v[218:221], v[104:107]
	ds_read_b128 v[206:209], v69 offset:20480
	s_waitcnt lgkmcnt(0)
	v_mfma_f32_16x16x32_bf16 v[124:127], v[206:209], v[202:205], v[124:127]
	v_mfma_f32_16x16x32_bf16 v[128:131], v[206:209], v[210:213], v[128:131]
	v_mfma_f32_16x16x32_bf16 v[164:167], v[206:209], v[214:217], v[164:167]
	v_mfma_f32_16x16x32_bf16 v[120:123], v[206:209], v[218:221], v[120:123]
	ds_read_b128 v[206:209], v69 offset:22528
	s_waitcnt vmcnt(0)
	s_waitcnt vmcnt(0) lgkmcnt(0)
	v_mfma_f32_16x16x32_bf16 v[76:79], v[206:209], v[202:205], v[76:79]
	s_barrier
	ds_read_b128 v[202:205], v68 offset:49152
	v_mfma_f32_16x16x32_bf16 v[84:87], v[206:209], v[210:213], v[84:87]
	ds_read_b128 v[210:213], v70 offset:34816
	ds_read_b128 v[242:245], v71 offset:34816
	ds_read_b128 v[246:249], v71 offset:36864
	v_mfma_f32_16x16x32_bf16 v[92:95], v[206:209], v[214:217], v[92:95]
	ds_read_b128 v[214:217], v70 offset:36864
	ds_read_b128 v[188:191], v71 offset:38912
	v_mfma_f32_16x16x32_bf16 v[100:103], v[206:209], v[218:221], v[100:103]
	ds_read_b128 v[206:209], v70 offset:32768
	ds_read_b128 v[218:221], v70 offset:38912
	s_waitcnt lgkmcnt(1)
	v_mfma_f32_16x16x32_bf16 v[80:83], v[202:205], v[206:209], v[80:83]
	v_mfma_f32_16x16x32_bf16 v[88:91], v[202:205], v[210:213], v[88:91]
	v_mfma_f32_16x16x32_bf16 v[96:99], v[202:205], v[214:217], v[96:99]
	s_waitcnt lgkmcnt(0)
	v_mfma_f32_16x16x32_bf16 v[72:75], v[202:205], v[218:221], v[72:75]
	ds_read_b128 v[202:205], v68 offset:51200
	s_waitcnt lgkmcnt(0)
	v_mfma_f32_16x16x32_bf16 v[108:111], v[202:205], v[206:209], v[108:111]
	v_mfma_f32_16x16x32_bf16 v[222:225], v[202:205], v[210:213], v[112:115]
	v_mfma_f32_16x16x32_bf16 v[226:229], v[202:205], v[214:217], v[116:119]
	v_mfma_f32_16x16x32_bf16 v[202:205], v[202:205], v[218:221], v[104:107]
	s_nop 2
	ds_read_b128 v[104:107], v68 offset:53248
	s_waitcnt lgkmcnt(0)
	v_mfma_f32_16x16x32_bf16 v[230:233], v[104:107], v[206:209], v[124:127]
	v_mfma_f32_16x16x32_bf16 v[234:237], v[104:107], v[210:213], v[128:131]
	v_mfma_f32_16x16x32_bf16 v[164:167], v[104:107], v[214:217], v[164:167]
	v_mfma_f32_16x16x32_bf16 v[238:241], v[104:107], v[218:221], v[120:123]
	ds_read_b128 v[104:107], v68 offset:55296
	s_waitcnt lgkmcnt(0)
	v_mfma_f32_16x16x32_bf16 v[76:79], v[104:107], v[206:209], v[76:79]
	v_mfma_f32_16x16x32_bf16 v[206:209], v[104:107], v[210:213], v[84:87]
	s_nop 2
	ds_read_b128 v[84:87], v69 offset:49152
	v_mfma_f32_16x16x32_bf16 v[210:213], v[104:107], v[214:217], v[92:95]
	v_mfma_f32_16x16x32_bf16 v[214:217], v[104:107], v[218:221], v[100:103]
	ds_read_b128 v[218:221], v71 offset:32768
	s_waitcnt lgkmcnt(1)
	v_mfma_f32_16x16x32_bf16 v[116:119], v[84:87], v[188:191], v[72:75]
	s_nop 2
	ds_read_b128 v[70:73], v69 offset:51200
	s_waitcnt lgkmcnt(0)
	v_mfma_f32_16x16x32_bf16 v[112:115], v[70:73], v[218:221], v[108:111]
	v_mfma_f32_16x16x32_bf16 v[108:111], v[70:73], v[242:245], v[222:225]
	v_mfma_f32_16x16x32_bf16 v[104:107], v[70:73], v[246:249], v[226:229]
	v_mfma_f32_16x16x32_bf16 v[100:103], v[70:73], v[188:191], v[202:205]
	ds_read_b128 v[70:73], v69 offset:53248
	v_mfma_f32_16x16x32_bf16 v[128:131], v[84:87], v[218:221], v[80:83]
	v_mfma_f32_16x16x32_bf16 v[124:127], v[84:87], v[242:245], v[88:91]
	v_mfma_f32_16x16x32_bf16 v[120:123], v[84:87], v[246:249], v[96:99]
	s_waitcnt lgkmcnt(0)
	v_mfma_f32_16x16x32_bf16 v[96:99], v[70:73], v[218:221], v[230:233]
	v_mfma_f32_16x16x32_bf16 v[92:95], v[70:73], v[242:245], v[234:237]
	v_mfma_f32_16x16x32_bf16 v[88:91], v[70:73], v[246:249], v[164:167]
	v_mfma_f32_16x16x32_bf16 v[84:87], v[70:73], v[188:191], v[238:241]
	ds_read_b128 v[68:71], v69 offset:55296
	s_waitcnt vmcnt(0)
	s_waitcnt lgkmcnt(0)
	v_mfma_f32_16x16x32_bf16 v[80:83], v[68:71], v[218:221], v[76:79]
	s_barrier
	v_mfma_f32_16x16x32_bf16 v[76:79], v[68:71], v[242:245], v[206:209]
	v_mfma_f32_16x16x32_bf16 v[72:75], v[68:71], v[246:249], v[210:213]
	v_mfma_f32_16x16x32_bf16 v[68:71], v[68:71], v[188:191], v[214:217]
	s_cmp_lg_u32 s66, 2
	s_cbranch_scc0 .LBB0_165
	s_lshl_b32 s2, s66, 10
	s_add_i32 s56, s41, s2
	v_mov_b32_e32 v163, v168
	s_mov_b64 s[60:61], 0
	s_mov_b64 s[58:59], -1
	s_branch .LBB0_166
